# loop-edge (7.11-style): next SEL tile-id LDS read issued before the loop-closing barrier so its latency overlaps the barrier wait
# baseline (speedup 1.0000x reference)
; template <int MODE> DI void attn_run(AttnCtx& c, const bf16x8 (&q)[8], f32x16 (&o)[4], ldsp lds, int tid, int wv) {
;     ...
;     for (int i = 0; i < c.ntiles; ++i) {
;         const int cur = i & 1, tj = TILE_ID(i);
;         const int m3n = STAG ? (m3 == 2 ? 0 : m3 + 1) : (m3 ^ 1);
;         float cb_next = 0.f;
;         if (MODE == MD_FOX || ((MODE == MD_SEL || MODE == MD_CMP1 || MODE == MD_CMP2) && c.xsel)) {
;             if (i > 0) {
;                 unsigned any = 0u;
; #pragma unroll
;                 for (int k = 0; k < NWAVES; ++k) any |= xflag[((i - 1) & 1) * NWAVES + k];
;                 if (any == 0u) break;
;             }
;             if (MODE == MD_FOX) { if (i + 1 < c.ntiles) cb_next = c.cumb[(size_t)TILE_ID(i + 1) * 64 + 63]; }
;             else if (MODE == MD_SEL) { if (i + 1 < c.ntiles) cb_next = -c.slope2 * (float)(c.t - (TILE_ID(i + 1) * 64 + 63)); }
;             else { if (i + 1 < c.ntiles) cb_next = -c.slope2 * (float)(c.t - (TILE_ID(i + 1) * 1024 + 1039)); }
;         }
;         if (i + 1 < c.ntiles) { const int tn = TILE_ID(i + 1);
.LBB0_897:
	s_and_b64 vcc, exec, s[2:3]
	s_waitcnt lgkmcnt(0)
	s_barrier
	s_cbranch_vccnz .LBB0_1056
	s_add_i32 s2, 0, 0x21a00
	v_subrev_u32_e32 v211, 63, v148
	v_lshl_add_u32 v212, v147, 4, s2
	v_mov_b32_e32 v147, v146
	v_add_u32_e32 v213, v206, v82
	s_mov_b32 s20, 1
	s_mov_b32 s21, 2
	s_mov_b32 s31, 8
	v_readlane_b32 s34, v254, 35
	s_nop 3
	s_add_i32 s2, s34, -4
	v_mov_b32_e32 v0, s2
	ds_read2_b32 v[144:145], v0 offset1:1
	s_mov_b32 s16, 1
.LBB0_899:
	s_and_b64 vcc, exec, s[54:55]
	s_waitcnt lgkmcnt(0)
	v_readfirstlane_b32 s22, v144
	s_cbranch_vccz .LBB0_925
	s_and_b32 s2, s31, 8
	s_xor_b32 s3, s2, 8
	s_add_i32 s4, 0, 0x22180
	s_lshl_b32 s3, s3, 2
	s_add_i32 s3, s4, s3
	v_mov_b32_e32 v0, s3
	ds_read_b128 v[130:133], v0
	ds_read_b128 v[134:137], v0 offset:16
	s_mov_b64 s[4:5], 0
	s_mov_b64 s[2:3], 0
	s_waitcnt lgkmcnt(0)
	v_or3_b32 v0, v130, v131, v132
	v_or3_b32 v2, v133, v134, v135
	v_or3_b32 v0, v0, v136, v137
	v_or_b32_e32 v0, v0, v2
	v_cmp_ne_u32_e32 vcc, 0, v0
	s_cbranch_vccz .LBB0_904
	s_cmp_ge_i32 s21, s30
	v_mov_b32_e32 v190, 0
	s_cbranch_scc1 .LBB0_903
	v_mov_b32_e32 v0, v145
	v_lshlrev_b32_e32 v0, 6, v0
	v_sub_u32_e32 v0, v211, v0
	v_cvt_f32_i32_e32 v0, v0
	v_mul_f32_e64 v190, -v146, v0

; template <int MODE> DI void attn_run(AttnCtx& c, const bf16x8 (&q)[8], f32x16 (&o)[4], ldsp lds, int tid, int wv) {
;     ...
;     for (int i = 0; i < c.ntiles; ++i) {
;         const int cur = i & 1, tj = TILE_ID(i);
;         const int m3n = STAG ? (m3 == 2 ? 0 : m3 + 1) : (m3 ^ 1);
;     ...
;         __syncthreads();
.LBB0_924:
	s_waitcnt lgkmcnt(0)
	v_mov_b32_e32 v0, s34
	ds_read2_b32 v[144:145], v0 offset1:1
	s_barrier
	s_add_i32 s34, s34, 4
	s_add_i32 s21, s21, 1
	s_add_i32 s31, s31, 8
	s_and_b64 vcc, exec, s[24:25]
	s_cbranch_vccz .LBB0_927
	s_branch .LBB0_1055
